# P5 epilogue: leading half runs its epilogue prologue and first row block before the align barrier (overlaps the trailing half's last MFMA segment)
# speedup vs baseline: 1.0021x; 1.0004x over previous
; #define PG8_STAGE(bufoff, gbase, voff) do { _Pragma("unroll") for (int _i = 0; _i < 2; ++_i) \
;         __builtin_amdgcn_global_load_lds((const unsigned*)((const char*)(gbase) + (voff)[_i]), (PG8_LAS unsigned*)(lds + (bufoff) + ldsw + _i * 8192), 16, 0, 0); } while (0)
; #define PG8_LDA(dst, b, h) do { _Pragma("unroll") for (int m = 0; m < 4; ++m) _Pragma("unroll") for (int k = 0; k < 2; ++k) dst[m][k] = *(const PG8_LAS bf16x8*)(lds + PG8_SA(b, h) + aoff + m * 2048 + k * 1024); } while (0)
; #define PG8_MMA(ai, bj, At, Bt) do { __builtin_amdgcn_s_setprio(1); _Pragma("unroll") for (int m = 0; m < 4; ++m) _Pragma("unroll") for (int n = 0; n < 2; ++n) _Pragma("unroll") for (int k = 0; k < 2; ++k) \
;         acc[ai][bj][m][n] = __builtin_amdgcn_mfma_f32_16x16x32_bf16(Bt[n][k], At[m][k], acc[ai][bj][m][n], 0, 0, 0); __builtin_amdgcn_s_setprio(0); } while (0)
; #define PG8_WAIT_V(n) asm volatile("s_waitcnt vmcnt(" #n ")" ::: "memory")
; #define PG8_WAIT_L(n) asm volatile("s_waitcnt lgkmcnt(" #n ")" ::: "memory")
; #define PG8_BAR __builtin_amdgcn_s_barrier()
; #define PG8_SCHED __builtin_amdgcn_sched_barrier(0)
; template <class Epi, class Sched, bool ALIGN_EPI = false, bool SP2 = false>
; __device__ __forceinline__ void gemm_phase(PG8_LAS unsigned char* lds, const Gemm g, const Sched& S, const Epi& E) {
;     ...
;             PG8_LDA(At, 1, 1); PG8_STAGE(PG8_SB(1, 0), b3, voffB); PG8_STAGE(PG8_SB(1, 1), b3 + hstep, voffB); PG8_STAGE(PG8_SA(1, 0), a3, voffA);
;             PG8_WAIT_V(8); PG8_WAIT_L(0); PG8_BAR; PG8_MMA(1, 0, At, B0); PG8_MMA(1, 1, At, B1); PG8_BAR; PG8_SCHED;
;     ...
;         if constexpr (ALIGN_EPI) { if (wr == 0) PG8_BAR; }
.Lnl_740_7:
	s_barrier
	s_waitcnt lgkmcnt(0)
	v_mfma_f32_16x16x32_bf16 v[62:65], v[156:159], v[188:191], v[62:65]
	v_mfma_f32_16x16x32_bf16 v[58:61], v[164:167], v[188:191], v[58:61]
	v_mfma_f32_16x16x32_bf16 v[46:49], v[156:159], v[196:199], v[46:49]
	v_mfma_f32_16x16x32_bf16 v[42:45], v[164:167], v[196:199], v[42:45]
	v_mfma_f32_16x16x32_bf16 v[30:33], v[156:159], v[208:211], v[30:33]
	v_mfma_f32_16x16x32_bf16 v[26:29], v[164:167], v[208:211], v[26:29]
	v_mfma_f32_16x16x32_bf16 v[14:17], v[156:159], v[216:219], v[14:17]
	v_mfma_f32_16x16x32_bf16 v[10:13], v[164:167], v[216:219], v[10:13]
	v_mfma_f32_16x16x32_bf16 v[62:65], v[160:163], v[192:195], v[62:65]
	v_mfma_f32_16x16x32_bf16 v[58:61], v[168:171], v[192:195], v[58:61]
	v_mfma_f32_16x16x32_bf16 v[46:49], v[160:163], v[200:203], v[46:49]
	v_mfma_f32_16x16x32_bf16 v[42:45], v[168:171], v[200:203], v[42:45]
	v_mfma_f32_16x16x32_bf16 v[30:33], v[160:163], v[212:215], v[30:33]
	v_mfma_f32_16x16x32_bf16 v[26:29], v[168:171], v[212:215], v[26:29]
	v_mfma_f32_16x16x32_bf16 v[14:17], v[160:163], v[220:223], v[14:17]
	v_mfma_f32_16x16x32_bf16 v[10:13], v[168:171], v[220:223], v[10:13]
	v_mfma_f32_16x16x32_bf16 v[54:57], v[172:175], v[188:191], v[54:57]
	v_mfma_f32_16x16x32_bf16 v[50:53], v[180:183], v[188:191], v[50:53]
	v_mfma_f32_16x16x32_bf16 v[38:41], v[172:175], v[196:199], v[38:41]
	v_mfma_f32_16x16x32_bf16 v[34:37], v[180:183], v[196:199], v[34:37]
	v_mfma_f32_16x16x32_bf16 v[22:25], v[172:175], v[208:211], v[22:25]
	v_mfma_f32_16x16x32_bf16 v[18:21], v[180:183], v[208:211], v[18:21]
	v_mfma_f32_16x16x32_bf16 v[6:9], v[172:175], v[216:219], v[6:9]
	v_mfma_f32_16x16x32_bf16 v[2:5], v[180:183], v[216:219], v[2:5]
	v_mfma_f32_16x16x32_bf16 v[54:57], v[176:179], v[192:195], v[54:57]
	v_mfma_f32_16x16x32_bf16 v[50:53], v[184:187], v[192:195], v[50:53]
	v_mfma_f32_16x16x32_bf16 v[38:41], v[176:179], v[200:203], v[38:41]
	v_mfma_f32_16x16x32_bf16 v[34:37], v[184:187], v[200:203], v[34:37]
	v_mfma_f32_16x16x32_bf16 v[22:25], v[176:179], v[212:215], v[22:25]
	v_mfma_f32_16x16x32_bf16 v[18:21], v[184:187], v[212:215], v[18:21]
	v_mfma_f32_16x16x32_bf16 v[6:9], v[176:179], v[220:223], v[6:9]
	v_mfma_f32_16x16x32_bf16 v[2:5], v[184:187], v[220:223], v[2:5]
	s_add_i32 s71, s71, 2
	s_add_u32 s30, s30, 0x100
	s_addc_u32 s31, s31, 0
	s_add_u32 s33, s33, 0x100
	s_addc_u32 s70, s70, 0
	s_cmp_gt_u32 s71, 13
	s_barrier
	s_cbranch_scc0 .LBB0_740


; #define PG8_BAR __builtin_amdgcn_s_barrier()
; template <class Epi, class Sched, bool ALIGN_EPI = false, bool SP2 = false>
; __device__ __forceinline__ void gemm_phase(PG8_LAS unsigned char* lds, const Gemm g, const Sched& S, const Epi& E) {
;     ...
;         if constexpr (ALIGN_EPI) { if (wr == 0) PG8_BAR; }
;     __device__ __forceinline__ void operator()(const f32x4 (&acc)[2][2][4][2], const Unit& u, int wr, int wc, int fr, int fq) const {
;     ...
;                 const int row = row0 + ai * HALF + m * 16;
;                 float rs;
;                 if (rsc) rs = rsc[row - rbase];
;                 else {
;                     const f32x4* pp = (const f32x4*)(part + (size_t)row * 16);
;                     const f32x4 p0 = pp[0], p1 = pp[1], p2 = pp[2], p3 = pp[3];
;                     const float ssq = ((p0[0] + p0[1]) + (p0[2] + p0[3])) + ((p1[0] + p1[1]) + (p1[2] + p1[3])) + ((p2[0] + p2[1]) + (p2[2] + p2[3])) + ((p3[0] + p3[1]) + (p3[2] + p3[3]));
;                     rs = __builtin_amdgcn_rsqf(ssq * (1.0f / 1024.0f) + 1e-6f);
.LBB0_743:
	v_mov_b32_e32 v184, 0xbfb8aa3b
	v_mov_b32_e32 v186, 1.0
	s_mov_b32 s100, 0x16000
	s_mov_b32 s101, 0
	s_mov_b32 s98, 0x6e000
	s_mov_b32 s99, 0
	v_lshl_add_u32 v148, s26, 8, v1
	s_mov_b64 s[26:27], -1
	s_and_b64 vcc, exec, s[36:37]
	v_ashrrev_i32_e32 v149, 31, v148
	s_cbranch_vccz .LBB0_745
	s_bitcmp1_b32 s14, 0
	s_cbranch_scc0 .Lgu_nb0
	s_barrier
.Lgu_nb0:
	v_lshlrev_b64 v[156:157], 6, v[148:149]
	v_lshl_add_u64 v[168:169], s[8:9], 0, v[156:157]
	global_load_dwordx4 v[156:159], v[168:169], off
	global_load_dwordx4 v[160:163], v[168:169], off offset:16
	global_load_dwordx4 v[164:167], v[168:169], off offset:32
	s_nop 0
	global_load_dwordx4 v[168:171], v[168:169], off offset:48
	s_mov_b64 s[26:27], 0
	s_waitcnt vmcnt(0)
	v_mov_b32_e32 v172, v157
	v_mov_b32_e32 v173, v158
	v_mov_b32_e32 v157, v159
	v_mov_b32_e32 v158, v161
	v_mov_b32_e32 v159, v162
	v_mov_b32_e32 v161, v163
	v_pk_add_f32 v[156:157], v[172:173], v[156:157]
	v_pk_add_f32 v[158:159], v[158:159], v[160:161]
	v_pk_add_f32 v[156:157], v[156:157], v[156:157] op_sel:[0,1] op_sel_hi:[1,0]
	v_pk_add_f32 v[158:159], v[158:159], v[158:159] op_sel:[0,1] op_sel_hi:[1,0]
	v_add_f32_e32 v162, v164, v165
	v_add_f32_e32 v164, v166, v167
	v_mov_b32_e32 v163, v170
	v_mov_b32_e32 v165, v171
	v_mov_b32_e32 v157, v168
	v_mov_b32_e32 v159, v169
	v_pk_add_f32 v[156:157], v[156:157], v[158:159]
	v_pk_add_f32 v[158:159], v[162:163], v[164:165]
	s_nop 0
	v_pk_add_f32 v[156:157], v[156:157], v[158:159]
	s_nop 0
	v_add_f32_e32 v150, v156, v157
	v_fmamk_f32 v150, v150, 0x3a800000, v155
	v_rsq_f32_e32 v150, v150

; __device__ __forceinline__ unsigned cvt_pk_bf16(float lo, float hi) { f32x2 v = {lo, hi}; return __builtin_bit_cast(unsigned, __builtin_convertvector(v, nbf16x2e)); }
; #define PG8_BAR __builtin_amdgcn_s_barrier()
; template <class Epi, class Sched, bool ALIGN_EPI = false, bool SP2 = false>
; __device__ __forceinline__ void gemm_phase(PG8_LAS unsigned char* lds, const Gemm g, const Sched& S, const Epi& E) {
;     ...
;         if constexpr (ALIGN_EPI) { if (wr == 0) PG8_BAR; }
;     __device__ __forceinline__ void operator()(const f32x4 (&acc)[2][2][4][2], const Unit& u, int wr, int wc, int fr, int fq) const {
;     ...
;                 float v[8];
; #pragma unroll
;                 for (int n = 0; n < 2; ++n)
; #pragma unroll
;                     for (int i = 0; i < 4; ++i) { const float g = acc[ai][0][m][n][i] * rs, up = acc[ai][1][m][n][i] * rs; v[4 * n + i] = g * __builtin_amdgcn_rcpf(1.0f + __expf(-g)) * up; }
;                 u32x4 w; w.x = cvt_pk_bf16(v[0], v[1]); w.y = cvt_pk_bf16(v[2], v[3]); w.z = cvt_pk_bf16(v[4], v[5]); w.w = cvt_pk_bf16(v[6], v[7]);
;                 *(u32x4*)(O + (size_t)row * 2816 + u.pn * HALF + wc * 32 + 8 * fq) = w;
.Lgu_fast:
	s_lshl_b32 s24, s24, 7
	s_ashr_i32 s25, s24, 31
	v_mov_b64_e32 v[236:237], s[34:35]
	v_mad_u64_u32 v[236:237], s[26:27], v148, s68, v[236:237]
	v_lshl_add_u64 v[236:237], s[24:25], 1, v[236:237]
	v_lshl_add_u64 v[236:237], v[236:237], 0, s[4:5]
	v_lshl_add_u64 v[236:237], v[236:237], 0, v[138:139]
	v_pk_mul_f32 v[126:127], v[126:127], v[228:229] op_sel_hi:[1,0]
	v_pk_mul_f32 v[128:129], v[128:129], v[228:229] op_sel_hi:[1,0]
	v_pk_mul_f32 v[122:123], v[122:123], v[228:229] op_sel_hi:[1,0]
	v_pk_mul_f32 v[124:125], v[124:125], v[228:229] op_sel_hi:[1,0]
	v_pk_mul_f32 v[176:177], v[126:127], v[184:185] op_sel_hi:[1,0]
	v_pk_mul_f32 v[178:179], v[128:129], v[184:185] op_sel_hi:[1,0]
	v_pk_mul_f32 v[180:181], v[122:123], v[184:185] op_sel_hi:[1,0]
	v_pk_mul_f32 v[182:183], v[124:125], v[184:185] op_sel_hi:[1,0]
	v_exp_f32_e32 v176, v176
	v_exp_f32_e32 v177, v177
	v_exp_f32_e32 v178, v178
	v_exp_f32_e32 v179, v179
	v_exp_f32_e32 v180, v180
	v_exp_f32_e32 v181, v181
	v_exp_f32_e32 v182, v182
	v_exp_f32_e32 v183, v183
	v_pk_add_f32 v[176:177], v[176:177], v[186:187] op_sel_hi:[1,0]
	v_pk_add_f32 v[178:179], v[178:179], v[186:187] op_sel_hi:[1,0]
	v_pk_add_f32 v[180:181], v[180:181], v[186:187] op_sel_hi:[1,0]
	v_pk_add_f32 v[182:183], v[182:183], v[186:187] op_sel_hi:[1,0]
	v_rcp_f32_e32 v176, v176
	v_rcp_f32_e32 v177, v177
	v_rcp_f32_e32 v178, v178
	v_rcp_f32_e32 v179, v179
	v_rcp_f32_e32 v180, v180
	v_rcp_f32_e32 v181, v181
	v_rcp_f32_e32 v182, v182
	v_rcp_f32_e32 v183, v183
	v_pk_mul_f32 v[118:119], v[118:119], v[228:229] op_sel_hi:[1,0]
	v_pk_mul_f32 v[120:121], v[120:121], v[228:229] op_sel_hi:[1,0]
	v_pk_mul_f32 v[114:115], v[114:115], v[228:229] op_sel_hi:[1,0]
	v_pk_mul_f32 v[116:117], v[116:117], v[228:229] op_sel_hi:[1,0]
	v_pk_mul_f32 v[126:127], v[126:127], v[176:177]
	v_pk_mul_f32 v[128:129], v[128:129], v[178:179]
	v_pk_mul_f32 v[122:123], v[122:123], v[180:181]
	v_pk_mul_f32 v[124:125], v[124:125], v[182:183]
	v_pk_mul_f32 v[118:119], v[118:119], v[126:127]
	v_pk_mul_f32 v[120:121], v[120:121], v[128:129]
	v_pk_mul_f32 v[122:123], v[114:115], v[122:123]
	v_pk_mul_f32 v[124:125], v[116:117], v[124:125]
	v_cvt_pk_bf16_f32 v114, v118, v119
	v_cvt_pk_bf16_f32 v115, v120, v121
	v_cvt_pk_bf16_f32 v116, v122, v123
	v_cvt_pk_bf16_f32 v117, v124, v125
	global_store_dwordx4 v[236:237], v[114:117], off
	s_bitcmp1_b32 s14, 0
	s_cbranch_scc0 .Lgu_nb1
	s_barrier
.Lgu_nb1:
	v_mov_b32_e32 v188, v229
	v_pk_mul_f32 v[110:111], v[110:111], v[188:189] op_sel_hi:[1,0]
	v_pk_mul_f32 v[112:113], v[112:113], v[188:189] op_sel_hi:[1,0]
	v_pk_mul_f32 v[106:107], v[106:107], v[188:189] op_sel_hi:[1,0]
	v_pk_mul_f32 v[108:109], v[108:109], v[188:189] op_sel_hi:[1,0]
	v_pk_mul_f32 v[176:177], v[110:111], v[184:185] op_sel_hi:[1,0]
	v_pk_mul_f32 v[178:179], v[112:113], v[184:185] op_sel_hi:[1,0]
	v_pk_mul_f32 v[180:181], v[106:107], v[184:185] op_sel_hi:[1,0]
	v_pk_mul_f32 v[182:183], v[108:109], v[184:185] op_sel_hi:[1,0]
	v_exp_f32_e32 v176, v176
	v_exp_f32_e32 v177, v177
	v_exp_f32_e32 v178, v178
	v_exp_f32_e32 v179, v179
	v_exp_f32_e32 v180, v180
	v_exp_f32_e32 v181, v181
	v_exp_f32_e32 v182, v182
	v_exp_f32_e32 v183, v183
	v_pk_add_f32 v[176:177], v[176:177], v[186:187] op_sel_hi:[1,0]
	v_pk_add_f32 v[178:179], v[178:179], v[186:187] op_sel_hi:[1,0]
	v_pk_add_f32 v[180:181], v[180:181], v[186:187] op_sel_hi:[1,0]
	v_pk_add_f32 v[182:183], v[182:183], v[186:187] op_sel_hi:[1,0]
	v_rcp_f32_e32 v176, v176
	v_rcp_f32_e32 v177, v177
	v_rcp_f32_e32 v178, v178
	v_rcp_f32_e32 v179, v179
	v_rcp_f32_e32 v180, v180
	v_rcp_f32_e32 v181, v181
	v_rcp_f32_e32 v182, v182
	v_rcp_f32_e32 v183, v183
	v_pk_mul_f32 v[102:103], v[102:103], v[188:189] op_sel_hi:[1,0]
	v_pk_mul_f32 v[104:105], v[104:105], v[188:189] op_sel_hi:[1,0]
	v_pk_mul_f32 v[98:99], v[98:99], v[188:189] op_sel_hi:[1,0]
	v_pk_mul_f32 v[100:101], v[100:101], v[188:189] op_sel_hi:[1,0]
	v_pk_mul_f32 v[110:111], v[110:111], v[176:177]
	v_pk_mul_f32 v[112:113], v[112:113], v[178:179]
	v_pk_mul_f32 v[106:107], v[106:107], v[180:181]
	v_pk_mul_f32 v[108:109], v[108:109], v[182:183]
	v_pk_mul_f32 v[102:103], v[102:103], v[110:111]
	v_pk_mul_f32 v[104:105], v[104:105], v[112:113]
	v_pk_mul_f32 v[106:107], v[98:99], v[106:107]
	v_pk_mul_f32 v[108:109], v[100:101], v[108:109]
	v_cvt_pk_bf16_f32 v98, v102, v103
	v_cvt_pk_bf16_f32 v99, v104, v105
	v_cvt_pk_bf16_f32 v100, v106, v107
	v_cvt_pk_bf16_f32 v101, v108, v109
	v_lshl_add_u64 v[236:237], v[236:237], 0, s[100:101]
	global_store_dwordx4 v[236:237], v[98:101], off
	v_pk_mul_f32 v[94:95], v[94:95], v[230:231] op_sel_hi:[1,0]
	v_pk_mul_f32 v[96:97], v[96:97], v[230:231] op_sel_hi:[1,0]
	v_pk_mul_f32 v[90:91], v[90:91], v[230:231] op_sel_hi:[1,0]
	v_pk_mul_f32 v[92:93], v[92:93], v[230:231] op_sel_hi:[1,0]
	v_pk_mul_f32 v[176:177], v[94:95], v[184:185] op_sel_hi:[1,0]
	v_pk_mul_f32 v[178:179], v[96:97], v[184:185] op_sel_hi:[1,0]
	v_pk_mul_f32 v[180:181], v[90:91], v[184:185] op_sel_hi:[1,0]
	v_pk_mul_f32 v[182:183], v[92:93], v[184:185] op_sel_hi:[1,0]
	v_exp_f32_e32 v176, v176
	v_exp_f32_e32 v177, v177
	v_exp_f32_e32 v178, v178
	v_exp_f32_e32 v179, v179
	v_exp_f32_e32 v180, v180
	v_exp_f32_e32 v181, v181
	v_exp_f32_e32 v182, v182
	v_exp_f32_e32 v183, v183
	v_pk_add_f32 v[176:177], v[176:177], v[186:187] op_sel_hi:[1,0]
	v_pk_add_f32 v[178:179], v[178:179], v[186:187] op_sel_hi:[1,0]
	v_pk_add_f32 v[180:181], v[180:181], v[186:187] op_sel_hi:[1,0]
	v_pk_add_f32 v[182:183], v[182:183], v[186:187] op_sel_hi:[1,0]
	v_rcp_f32_e32 v176, v176
	v_rcp_f32_e32 v177, v177
	v_rcp_f32_e32 v178, v178
	v_rcp_f32_e32 v179, v179
	v_rcp_f32_e32 v180, v180
; __device__ __forceinline__ unsigned cvt_pk_bf16(float lo, float hi) { f32x2 v = {lo, hi}; return __builtin_bit_cast(unsigned, __builtin_convertvector(v, nbf16x2e)); }
;     __device__ __forceinline__ void operator()(const f32x4 (&acc)[2][2][4][2], const Unit& u, int wr, int wc, int fr, int fq) const {
;     ...
;                 float v[8];
; #pragma unroll
;                 for (int n = 0; n < 2; ++n)
; #pragma unroll
;                     for (int i = 0; i < 4; ++i) { const float g = acc[ai][0][m][n][i] * rs, up = acc[ai][1][m][n][i] * rs; v[4 * n + i] = g * __builtin_amdgcn_rcpf(1.0f + __expf(-g)) * up; }
;                 u32x4 w; w.x = cvt_pk_bf16(v[0], v[1]); w.y = cvt_pk_bf16(v[2], v[3]); w.z = cvt_pk_bf16(v[4], v[5]); w.w = cvt_pk_bf16(v[6], v[7]);
;                 *(u32x4*)(O + (size_t)row * 2816 + u.pn * HALF + wc * 32 + 8 * fq) = w;
	v_rcp_f32_e32 v181, v181
	v_rcp_f32_e32 v182, v182
	v_rcp_f32_e32 v183, v183
	v_pk_mul_f32 v[86:87], v[86:87], v[230:231] op_sel_hi:[1,0]
	v_pk_mul_f32 v[88:89], v[88:89], v[230:231] op_sel_hi:[1,0]
	v_pk_mul_f32 v[82:83], v[82:83], v[230:231] op_sel_hi:[1,0]
	v_pk_mul_f32 v[84:85], v[84:85], v[230:231] op_sel_hi:[1,0]
	v_pk_mul_f32 v[94:95], v[94:95], v[176:177]
	v_pk_mul_f32 v[96:97], v[96:97], v[178:179]
	v_pk_mul_f32 v[90:91], v[90:91], v[180:181]
	v_pk_mul_f32 v[92:93], v[92:93], v[182:183]
	v_pk_mul_f32 v[86:87], v[86:87], v[94:95]
	v_pk_mul_f32 v[88:89], v[88:89], v[96:97]
	v_pk_mul_f32 v[90:91], v[82:83], v[90:91]
	v_pk_mul_f32 v[92:93], v[84:85], v[92:93]
	v_cvt_pk_bf16_f32 v82, v86, v87
	v_cvt_pk_bf16_f32 v83, v88, v89
	v_cvt_pk_bf16_f32 v84, v90, v91
	v_cvt_pk_bf16_f32 v85, v92, v93
	v_lshl_add_u64 v[236:237], v[236:237], 0, s[100:101]
	global_store_dwordx4 v[236:237], v[82:85], off
	v_mov_b32_e32 v188, v231
	v_pk_mul_f32 v[78:79], v[78:79], v[188:189] op_sel_hi:[1,0]
	v_pk_mul_f32 v[80:81], v[80:81], v[188:189] op_sel_hi:[1,0]
	v_pk_mul_f32 v[74:75], v[74:75], v[188:189] op_sel_hi:[1,0]
	v_pk_mul_f32 v[76:77], v[76:77], v[188:189] op_sel_hi:[1,0]
	v_pk_mul_f32 v[176:177], v[78:79], v[184:185] op_sel_hi:[1,0]
	v_pk_mul_f32 v[178:179], v[80:81], v[184:185] op_sel_hi:[1,0]
	v_pk_mul_f32 v[180:181], v[74:75], v[184:185] op_sel_hi:[1,0]
	v_pk_mul_f32 v[182:183], v[76:77], v[184:185] op_sel_hi:[1,0]
	v_exp_f32_e32 v176, v176
	v_exp_f32_e32 v177, v177
	v_exp_f32_e32 v178, v178
	v_exp_f32_e32 v179, v179
	v_exp_f32_e32 v180, v180
	v_exp_f32_e32 v181, v181
	v_exp_f32_e32 v182, v182
	v_exp_f32_e32 v183, v183
	v_pk_add_f32 v[176:177], v[176:177], v[186:187] op_sel_hi:[1,0]
	v_pk_add_f32 v[178:179], v[178:179], v[186:187] op_sel_hi:[1,0]
	v_pk_add_f32 v[180:181], v[180:181], v[186:187] op_sel_hi:[1,0]
	v_pk_add_f32 v[182:183], v[182:183], v[186:187] op_sel_hi:[1,0]
	v_rcp_f32_e32 v176, v176
	v_rcp_f32_e32 v177, v177
	v_rcp_f32_e32 v178, v178
	v_rcp_f32_e32 v179, v179
	v_rcp_f32_e32 v180, v180
	v_rcp_f32_e32 v181, v181
	v_rcp_f32_e32 v182, v182
	v_rcp_f32_e32 v183, v183
	v_pk_mul_f32 v[70:71], v[70:71], v[188:189] op_sel_hi:[1,0]
	v_pk_mul_f32 v[72:73], v[72:73], v[188:189] op_sel_hi:[1,0]
	v_pk_mul_f32 v[66:67], v[66:67], v[188:189] op_sel_hi:[1,0]
	v_pk_mul_f32 v[68:69], v[68:69], v[188:189] op_sel_hi:[1,0]
	v_pk_mul_f32 v[78:79], v[78:79], v[176:177]
	v_pk_mul_f32 v[80:81], v[80:81], v[178:179]
	v_pk_mul_f32 v[74:75], v[74:75], v[180:181]
	v_pk_mul_f32 v[76:77], v[76:77], v[182:183]
	v_pk_mul_f32 v[70:71], v[70:71], v[78:79]
	v_pk_mul_f32 v[72:73], v[72:73], v[80:81]
	v_pk_mul_f32 v[74:75], v[66:67], v[74:75]
	v_pk_mul_f32 v[76:77], v[68:69], v[76:77]
	v_cvt_pk_bf16_f32 v66, v70, v71
	v_cvt_pk_bf16_f32 v67, v72, v73
	v_cvt_pk_bf16_f32 v68, v74, v75
	v_cvt_pk_bf16_f32 v69, v76, v77
	v_lshl_add_u64 v[236:237], v[236:237], 0, s[100:101]
	global_store_dwordx4 v[236:237], v[66:69], off
	v_pk_mul_f32 v[62:63], v[62:63], v[232:233] op_sel_hi:[1,0]
	v_pk_mul_f32 v[64:65], v[64:65], v[232:233] op_sel_hi:[1,0]
	v_pk_mul_f32 v[58:59], v[58:59], v[232:233] op_sel_hi:[1,0]
	v_pk_mul_f32 v[60:61], v[60:61], v[232:233] op_sel_hi:[1,0]
	v_pk_mul_f32 v[176:177], v[62:63], v[184:185] op_sel_hi:[1,0]
	v_pk_mul_f32 v[178:179], v[64:65], v[184:185] op_sel_hi:[1,0]
	v_pk_mul_f32 v[180:181], v[58:59], v[184:185] op_sel_hi:[1,0]
	v_pk_mul_f32 v[182:183], v[60:61], v[184:185] op_sel_hi:[1,0]
	v_exp_f32_e32 v176, v176
	v_exp_f32_e32 v177, v177
	v_exp_f32_e32 v178, v178
	v_exp_f32_e32 v179, v179
	v_exp_f32_e32 v180, v180
	v_exp_f32_e32 v181, v181
	v_exp_f32_e32 v182, v182
	v_exp_f32_e32 v183, v183
	v_pk_add_f32 v[176:177], v[176:177], v[186:187] op_sel_hi:[1,0]
	v_pk_add_f32 v[178:179], v[178:179], v[186:187] op_sel_hi:[1,0]
	v_pk_add_f32 v[180:181], v[180:181], v[186:187] op_sel_hi:[1,0]
	v_pk_add_f32 v[182:183], v[182:183], v[186:187] op_sel_hi:[1,0]
	v_rcp_f32_e32 v176, v176
	v_rcp_f32_e32 v177, v177
	v_rcp_f32_e32 v178, v178
	v_rcp_f32_e32 v179, v179
	v_rcp_f32_e32 v180, v180
	v_rcp_f32_e32 v181, v181
	v_rcp_f32_e32 v182, v182
	v_rcp_f32_e32 v183, v183
	v_pk_mul_f32 v[54:55], v[54:55], v[232:233] op_sel_hi:[1,0]
	v_pk_mul_f32 v[56:57], v[56:57], v[232:233] op_sel_hi:[1,0]
	v_pk_mul_f32 v[50:51], v[50:51], v[232:233] op_sel_hi:[1,0]
	v_pk_mul_f32 v[52:53], v[52:53], v[232:233] op_sel_hi:[1,0]
	v_pk_mul_f32 v[62:63], v[62:63], v[176:177]
	v_pk_mul_f32 v[64:65], v[64:65], v[178:179]
	v_pk_mul_f32 v[58:59], v[58:59], v[180:181]
	v_pk_mul_f32 v[60:61], v[60:61], v[182:183]
	v_pk_mul_f32 v[54:55], v[54:55], v[62:63]
	v_pk_mul_f32 v[56:57], v[56:57], v[64:65]
	v_pk_mul_f32 v[58:59], v[50:51], v[58:59]
	v_pk_mul_f32 v[60:61], v[52:53], v[60:61]
	v_cvt_pk_bf16_f32 v50, v54, v55
	v_cvt_pk_bf16_f32 v51, v56, v57
	v_cvt_pk_bf16_f32 v52, v58, v59
	v_cvt_pk_bf16_f32 v53, v60, v61
	v_lshl_add_u64 v[236:237], v[236:237], 0, s[98:99]
	global_store_dwordx4 v[236:237], v[50:53], off
	v_mov_b32_e32 v188, v233
	v_pk_mul_f32 v[46:47], v[46:47], v[188:189] op_sel_hi:[1,0]
	v_pk_mul_f32 v[48:49], v[48:49], v[188:189] op_sel_hi:[1,0]
	v_pk_mul_f32 v[42:43], v[42:43], v[188:189] op_sel_hi:[1,0]
	v_pk_mul_f32 v[44:45], v[44:45], v[188:189] op_sel_hi:[1,0]
	v_pk_mul_f32 v[176:177], v[46:47], v[184:185] op_sel_hi:[1,0]
	v_pk_mul_f32 v[178:179], v[48:49], v[184:185] op_sel_hi:[1,0]
	v_pk_mul_f32 v[180:181], v[42:43], v[184:185] op_sel_hi:[1,0]
	v_pk_mul_f32 v[182:183], v[44:45], v[184:185] op_sel_hi:[1,0]
	v_exp_f32_e32 v176, v176
	v_exp_f32_e32 v177, v177
; __device__ __forceinline__ unsigned cvt_pk_bf16(float lo, float hi) { f32x2 v = {lo, hi}; return __builtin_bit_cast(unsigned, __builtin_convertvector(v, nbf16x2e)); }
;     __device__ __forceinline__ void operator()(const f32x4 (&acc)[2][2][4][2], const Unit& u, int wr, int wc, int fr, int fq) const {
;     ...
;                 float v[8];
; #pragma unroll
;                 for (int n = 0; n < 2; ++n)
; #pragma unroll
;                     for (int i = 0; i < 4; ++i) { const float g = acc[ai][0][m][n][i] * rs, up = acc[ai][1][m][n][i] * rs; v[4 * n + i] = g * __builtin_amdgcn_rcpf(1.0f + __expf(-g)) * up; }
;                 u32x4 w; w.x = cvt_pk_bf16(v[0], v[1]); w.y = cvt_pk_bf16(v[2], v[3]); w.z = cvt_pk_bf16(v[4], v[5]); w.w = cvt_pk_bf16(v[6], v[7]);
;                 *(u32x4*)(O + (size_t)row * 2816 + u.pn * HALF + wc * 32 + 8 * fq) = w;
	v_exp_f32_e32 v178, v178
	v_exp_f32_e32 v179, v179
	v_exp_f32_e32 v180, v180
	v_exp_f32_e32 v181, v181
	v_exp_f32_e32 v182, v182
	v_exp_f32_e32 v183, v183
	v_pk_add_f32 v[176:177], v[176:177], v[186:187] op_sel_hi:[1,0]
	v_pk_add_f32 v[178:179], v[178:179], v[186:187] op_sel_hi:[1,0]
	v_pk_add_f32 v[180:181], v[180:181], v[186:187] op_sel_hi:[1,0]
	v_pk_add_f32 v[182:183], v[182:183], v[186:187] op_sel_hi:[1,0]
	v_rcp_f32_e32 v176, v176
	v_rcp_f32_e32 v177, v177
	v_rcp_f32_e32 v178, v178
	v_rcp_f32_e32 v179, v179
	v_rcp_f32_e32 v180, v180
	v_rcp_f32_e32 v181, v181
	v_rcp_f32_e32 v182, v182
	v_rcp_f32_e32 v183, v183
	v_pk_mul_f32 v[38:39], v[38:39], v[188:189] op_sel_hi:[1,0]
	v_pk_mul_f32 v[40:41], v[40:41], v[188:189] op_sel_hi:[1,0]
	v_pk_mul_f32 v[34:35], v[34:35], v[188:189] op_sel_hi:[1,0]
	v_pk_mul_f32 v[36:37], v[36:37], v[188:189] op_sel_hi:[1,0]
	v_pk_mul_f32 v[46:47], v[46:47], v[176:177]
	v_pk_mul_f32 v[48:49], v[48:49], v[178:179]
	v_pk_mul_f32 v[42:43], v[42:43], v[180:181]
	v_pk_mul_f32 v[44:45], v[44:45], v[182:183]
	v_pk_mul_f32 v[38:39], v[38:39], v[46:47]
	v_pk_mul_f32 v[40:41], v[40:41], v[48:49]
	v_pk_mul_f32 v[42:43], v[34:35], v[42:43]
	v_pk_mul_f32 v[44:45], v[36:37], v[44:45]
	v_cvt_pk_bf16_f32 v34, v38, v39
	v_cvt_pk_bf16_f32 v35, v40, v41
	v_cvt_pk_bf16_f32 v36, v42, v43
	v_cvt_pk_bf16_f32 v37, v44, v45
	v_lshl_add_u64 v[236:237], v[236:237], 0, s[100:101]
	global_store_dwordx4 v[236:237], v[34:37], off
	v_pk_mul_f32 v[30:31], v[30:31], v[234:235] op_sel_hi:[1,0]
	v_pk_mul_f32 v[32:33], v[32:33], v[234:235] op_sel_hi:[1,0]
	v_pk_mul_f32 v[26:27], v[26:27], v[234:235] op_sel_hi:[1,0]
	v_pk_mul_f32 v[28:29], v[28:29], v[234:235] op_sel_hi:[1,0]
	v_pk_mul_f32 v[176:177], v[30:31], v[184:185] op_sel_hi:[1,0]
	v_pk_mul_f32 v[178:179], v[32:33], v[184:185] op_sel_hi:[1,0]
	v_pk_mul_f32 v[180:181], v[26:27], v[184:185] op_sel_hi:[1,0]
	v_pk_mul_f32 v[182:183], v[28:29], v[184:185] op_sel_hi:[1,0]
	v_exp_f32_e32 v176, v176
	v_exp_f32_e32 v177, v177
	v_exp_f32_e32 v178, v178
	v_exp_f32_e32 v179, v179
	v_exp_f32_e32 v180, v180
	v_exp_f32_e32 v181, v181
	v_exp_f32_e32 v182, v182
	v_exp_f32_e32 v183, v183
	v_pk_add_f32 v[176:177], v[176:177], v[186:187] op_sel_hi:[1,0]
	v_pk_add_f32 v[178:179], v[178:179], v[186:187] op_sel_hi:[1,0]
	v_pk_add_f32 v[180:181], v[180:181], v[186:187] op_sel_hi:[1,0]
	v_pk_add_f32 v[182:183], v[182:183], v[186:187] op_sel_hi:[1,0]
	v_rcp_f32_e32 v176, v176
	v_rcp_f32_e32 v177, v177
	v_rcp_f32_e32 v178, v178
	v_rcp_f32_e32 v179, v179
	v_rcp_f32_e32 v180, v180
	v_rcp_f32_e32 v181, v181
	v_rcp_f32_e32 v182, v182
	v_rcp_f32_e32 v183, v183
	v_pk_mul_f32 v[22:23], v[22:23], v[234:235] op_sel_hi:[1,0]
	v_pk_mul_f32 v[24:25], v[24:25], v[234:235] op_sel_hi:[1,0]
	v_pk_mul_f32 v[18:19], v[18:19], v[234:235] op_sel_hi:[1,0]
	v_pk_mul_f32 v[20:21], v[20:21], v[234:235] op_sel_hi:[1,0]
	v_pk_mul_f32 v[30:31], v[30:31], v[176:177]
	v_pk_mul_f32 v[32:33], v[32:33], v[178:179]
	v_pk_mul_f32 v[26:27], v[26:27], v[180:181]
	v_pk_mul_f32 v[28:29], v[28:29], v[182:183]
	v_pk_mul_f32 v[22:23], v[22:23], v[30:31]
	v_pk_mul_f32 v[24:25], v[24:25], v[32:33]
	v_pk_mul_f32 v[26:27], v[18:19], v[26:27]
	v_pk_mul_f32 v[28:29], v[20:21], v[28:29]
	v_cvt_pk_bf16_f32 v18, v22, v23
	v_cvt_pk_bf16_f32 v19, v24, v25
	v_cvt_pk_bf16_f32 v20, v26, v27
	v_cvt_pk_bf16_f32 v21, v28, v29
	v_lshl_add_u64 v[236:237], v[236:237], 0, s[100:101]
	global_store_dwordx4 v[236:237], v[18:21], off
	v_mov_b32_e32 v188, v235
	v_pk_mul_f32 v[14:15], v[14:15], v[188:189] op_sel_hi:[1,0]
	v_pk_mul_f32 v[16:17], v[16:17], v[188:189] op_sel_hi:[1,0]
	v_pk_mul_f32 v[10:11], v[10:11], v[188:189] op_sel_hi:[1,0]
	v_pk_mul_f32 v[12:13], v[12:13], v[188:189] op_sel_hi:[1,0]
	v_pk_mul_f32 v[176:177], v[14:15], v[184:185] op_sel_hi:[1,0]
	v_pk_mul_f32 v[178:179], v[16:17], v[184:185] op_sel_hi:[1,0]
	v_pk_mul_f32 v[180:181], v[10:11], v[184:185] op_sel_hi:[1,0]
	v_pk_mul_f32 v[182:183], v[12:13], v[184:185] op_sel_hi:[1,0]
	v_exp_f32_e32 v176, v176
	v_exp_f32_e32 v177, v177
	v_exp_f32_e32 v178, v178
	v_exp_f32_e32 v179, v179
	v_exp_f32_e32 v180, v180
	v_exp_f32_e32 v181, v181
	v_exp_f32_e32 v182, v182
	v_exp_f32_e32 v183, v183
	v_pk_add_f32 v[176:177], v[176:177], v[186:187] op_sel_hi:[1,0]
	v_pk_add_f32 v[178:179], v[178:179], v[186:187] op_sel_hi:[1,0]
	v_pk_add_f32 v[180:181], v[180:181], v[186:187] op_sel_hi:[1,0]
	v_pk_add_f32 v[182:183], v[182:183], v[186:187] op_sel_hi:[1,0]
	v_rcp_f32_e32 v176, v176
	v_rcp_f32_e32 v177, v177
	v_rcp_f32_e32 v178, v178
	v_rcp_f32_e32 v179, v179
	v_rcp_f32_e32 v180, v180
	v_rcp_f32_e32 v181, v181
	v_rcp_f32_e32 v182, v182
	v_rcp_f32_e32 v183, v183
	v_pk_mul_f32 v[6:7], v[6:7], v[188:189] op_sel_hi:[1,0]
	v_pk_mul_f32 v[8:9], v[8:9], v[188:189] op_sel_hi:[1,0]
	v_pk_mul_f32 v[2:3], v[2:3], v[188:189] op_sel_hi:[1,0]
	v_pk_mul_f32 v[4:5], v[4:5], v[188:189] op_sel_hi:[1,0]
	v_pk_mul_f32 v[14:15], v[14:15], v[176:177]
	v_pk_mul_f32 v[16:17], v[16:17], v[178:179]
	v_pk_mul_f32 v[10:11], v[10:11], v[180:181]
	v_pk_mul_f32 v[12:13], v[12:13], v[182:183]
	v_pk_mul_f32 v[6:7], v[6:7], v[14:15]
	v_pk_mul_f32 v[8:9], v[8:9], v[16:17]
	v_pk_mul_f32 v[10:11], v[2:3], v[10:11]
	v_pk_mul_f32 v[12:13], v[4:5], v[12:13]
	v_cvt_pk_bf16_f32 v2, v6, v7
	v_cvt_pk_bf16_f32 v3, v8, v9
	v_cvt_pk_bf16_f32 v4, v10, v11
	v_cvt_pk_bf16_f32 v5, v12, v13
	v_lshl_add_u64 v[236:237], v[236:237], 0, s[100:101]
	s_andn2_b64 vcc, exec, s[0:1]
	s_mov_b64 s[0:1], -1
	global_store_dwordx4 v[236:237], v[2:5], off
	s_branch .Lgu_done
